# static first tickets in the P3/P4 work queues (no atomic/LDS broadcast for the 2+5 uniform units per workgroup) + attention row-max chain without redundant self-max ops + mods GEMV 32 loads in flight
# speedup vs baseline: 1.0152x; 1.0098x over previous
.LBB0_286:
	v_mov_b32_e32 v62, v196
	s_barrier
	s_lshl_b64 s[2:3], s[46:47], 2
	v_readfirstlane_b32 s50, v62
	s_ashr_i32 s44, s50, 6
	v_readlane_b32 s4, v253, 0
	v_readlane_b32 s5, v253, 1
	s_add_u32 s2, s4, s2
	s_addc_u32 s3, s5, s3
	v_and_b32_e32 v64, 63, v62
	v_writelane_b32 v252, s2, 14
	v_lshlrev_b32_e32 v0, 2, v64
	v_and_b32_e32 v2, 7, v62
	v_writelane_b32 v252, s3, 15
	v_readlane_b32 s2, v254, 47
	v_ashrrev_i32_e32 v71, 3, v62
	v_and_b32_e32 v3, 15, v62
	v_add_u32_e32 v65, s2, v0
	v_readlane_b32 s2, v252, 9
	s_lshl_b32 s2, s2, 1
	v_readlane_b32 s3, v252, 10
	v_writelane_b32 v252, s2, 16
	s_movk_i32 s2, 0x800
	v_cmp_gt_i32_e64 s[38:39], s2, v62
	s_lshl_b32 s2, s44, 5
	v_lshlrev_b32_e32 v68, 3, v2
	s_and_b32 s2, s2, 32
	v_and_b32_e32 v5, 48, v62
	s_lshl_b32 s3, s44, 3
	v_or_b32_e32 v7, s2, v3
	s_lshl_b32 s2, s2, 2
	v_add_u32_e32 v8, 0, v0
	v_bitop3_b32 v0, v71, v68, 56 bitop3:0x6c
	v_lshlrev_b32_e32 v9, 1, v71
	v_lshlrev_b32_e32 v70, 4, v2
	v_add_u32_e32 v84, 0, v5
	s_and_b32 s3, s3, 0x3ffffff0
	v_lshrrev_b32_e32 v5, 2, v62
	v_lshlrev_b32_e32 v6, 2, v3
	s_add_i32 s2, s2, 0
	v_lshlrev_b32_e32 v0, 1, v0
	v_and_b32_e32 v9, 14, v9
	v_lshlrev_b32_e32 v11, 5, v2
	v_bfi_b32 v73, -16, v71, v62
	v_and_or_b32 v5, v5, 12, s3
	v_add_u32_e32 v87, s2, v6
	s_movk_i32 s2, 0x104
	v_add3_u32 v10, 0, v0, v9
	v_add_u32_e32 v72, 0, v11
	v_bitop3_b32 v0, v70, 56, v71 bitop3:0x48
	v_mul_lo_u32 v5, v5, s2
	v_mad_u64_u32 v[74:75], s[2:3], v71, s2, v[72:73]
	v_mul_u32_u24_e32 v12, 0x480, v2
	v_lshl_add_u32 v0, v0, 1, 0
	v_mul_u32_u24_e32 v2, 0x900, v2
	v_add3_u32 v75, v0, v2, v9
	v_or_b32_e32 v0, 8, v70
	v_bitop3_b32 v2, v0, 56, v71 bitop3:0x48
	v_lshl_add_u32 v2, v2, 1, 0
	v_mul_u32_u24_e32 v0, 0x90, v0
	v_lshrrev_b32_e32 v4, 1, v62
	v_add3_u32 v88, v2, v0, v9
	v_lshl_or_b32 v0, s44, 4, v3
	s_movk_i32 s2, 0x90
	v_and_b32_e32 v66, 24, v4
	v_readlane_b32 s45, v254, 48
	v_mul_lo_u32 v2, v0, s2
	v_add_u32_e32 v2, 0, v2
	v_add_u32_e32 v92, s45, v6
	v_bitop3_b32 v6, v0, v66, 56 bitop3:0x6c
	v_and_b32_e32 v9, 8, v62
	v_lshl_add_u32 v93, v6, 1, v2
	v_mad_u32_u24 v6, v3, s2, 0
	v_bitop3_b32 v15, v4, v9, 24 bitop3:0x6c
	v_lshl_add_u32 v94, v15, 1, v6
	v_or_b32_e32 v15, 32, v66
	v_bitop3_b32 v0, v0, v15, 56 bitop3:0x6c
	v_lshl_add_u32 v95, v0, 1, v2
	v_bitop3_b32 v0, v66, v9, 32 bitop3:0x36
	v_lshl_add_u32 v96, v0, 1, v6
	v_or_b32_e32 v0, 16, v3
	v_add_u32_e32 v2, 0x900, v6
	v_bitop3_b32 v9, v3, 24, 16 bitop3:0xc8
	v_bitop3_b32 v0, v0, v4, 24 bitop3:0x28
	v_lshl_add_u32 v97, v0, 1, v2
	v_bitop3_b32 v0, v66, v9, 32 bitop3:0x36
	v_lshl_add_u32 v98, v0, 1, v2
	v_or_b32_e32 v0, 32, v3
	v_add_u32_e32 v2, 0x1200, v6
	v_bitop3_b32 v3, v3, 40, 32 bitop3:0xc8
	v_bitop3_b32 v0, v0, v66, 40 bitop3:0x6c
	s_lshl_b32 s67, s44, 8
	v_lshl_add_u32 v99, v0, 1, v2
	v_bitop3_b32 v0, v66, v3, 32 bitop3:0x36
	v_lshl_add_u32 v100, v0, 1, v2
	v_or_b32_e32 v0, 48, v64
	s_cmp_lt_i32 s44, 0
	v_mad_u32_u24 v2, v0, s2, 0
	s_cselect_b64 s[2:3], -1, 0
	s_cmp_gt_i32 s44, 0
	s_cselect_b64 s[4:5], -1, 0
	s_cmp_lt_i32 s44, 1
	s_cselect_b64 s[6:7], -1, 0
	s_cmp_gt_i32 s44, 1
	s_cselect_b64 s[8:9], -1, 0
	s_cmp_lt_i32 s44, 2
	s_cselect_b64 s[10:11], -1, 0
	s_cmp_gt_i32 s44, 2
	s_cselect_b64 s[12:13], -1, 0
	s_cmp_lt_i32 s44, 3
	s_cselect_b64 s[14:15], -1, 0
	s_cmp_gt_i32 s44, 3
	s_cselect_b64 s[18:19], -1, 0
	s_cmp_lt_i32 s44, 4
	s_cselect_b64 s[20:21], -1, 0
	s_cmp_gt_i32 s44, 4
	s_cselect_b64 s[22:23], -1, 0
	s_cmp_lt_i32 s44, 5
	s_cselect_b64 s[24:25], -1, 0
	s_cmp_gt_i32 s44, 5
	s_cselect_b64 s[26:27], -1, 0
	s_cmp_lt_i32 s44, 6
	s_cselect_b64 s[28:29], -1, 0
	s_cmp_gt_i32 s44, 6
	s_cselect_b64 s[30:31], -1, 0
	s_cmp_lt_i32 s44, 7
	v_or_b32_e32 v13, 1, v68
	s_cselect_b64 s[34:35], -1, 0
	s_cmp_gt_i32 s44, 7
	s_cselect_b64 s[36:37], -1, 0
	v_add_u32_e32 v103, s45, v11
	v_lshl_add_u32 v104, v13, 2, s45
	s_ashr_i32 s45, s44, 31
	s_lshl_b64 s[48:49], s[44:45], 12
	v_lshlrev_b32_e32 v85, 6, v7
	v_bitop3_b32 v3, v64, 56, 48 bitop3:0xc8
	s_cmp_lt_u32 s50, 64
	v_lshl_add_u32 v86, v7, 2, 0
	v_or_b32_e32 v7, 0x400, v85
	s_mul_i32 s46, s44, 0x820
	v_mul_u32_u24_e32 v14, 0x90, v13
	v_bitop3_b32 v4, v0, v66, 56 bitop3:0x6c
	v_bitop3_b32 v3, v66, v3, 32 bitop3:0x36
	s_cselect_b64 s[44:45], -1, 0
	v_cmp_gt_u32_e32 vcc, 16, v64
	v_and_b32_e32 v67, 31, v62
	v_cmp_gt_i32_e64 s[40:41], 64, v62
	v_lshl_add_u32 v69, v62, 2, 0
	v_ashrrev_i32_e32 v63, 31, v62
	v_cmp_lt_u32_e64 s[42:43], 7, v62
	v_add_u32_e32 v89, 0x120, v88
	v_add_u32_e32 v90, 0x240, v88
	v_add_u32_e32 v91, 0x360, v88
	v_lshl_add_u32 v101, v4, 1, v2
	v_lshl_add_u32 v102, v3, 1, v2
	v_add_u32_e32 v105, 8, v103
	v_add_u32_e32 v106, 12, v103
	v_add_u32_e32 v107, 16, v103
	v_add_u32_e32 v108, 20, v103
	v_add_u32_e32 v109, 24, v103
	v_add_u32_e32 v110, 28, v103
	s_and_b64 s[50:51], s[44:45], vcc
	v_lshl_add_u32 v111, v62, 1, 0
	v_add_u32_e32 v112, v87, v5
	v_add_u32_e32 v113, v84, v7
	v_add_u32_e32 v114, v10, v12
	v_lshlrev_b32_e32 v115, 2, v0
	v_add_u32_e32 v116, s46, v8
	v_add_u32_e32 v117, v10, v14
	s_load_dwordx2 s[100:101], s[0:1], 0xe0
	s_waitcnt lgkmcnt(0)
	s_cmp_eq_u32 s100, 0x100
	s_cselect_b32 s101, 1, 0
	s_cselect_b32 s100, 0, 2
	s_branch .LBB0_289

.LBB0_289:
	s_barrier
	s_cmp_lt_u32 s100, 2
	s_cbranch_scc0 .Lq3_dyn
	v_readlane_b32 s46, v254, 56
	s_lshl_b32 s44, s100, 8
	s_add_i32 s46, s46, s44
	s_add_i32 s100, s100, 1
	s_add_i32 s83, 0, 0x23fc0
	s_mov_b64 s[44:45], -1
	s_branch .Lq3_have_u
.Lq3_dyn:
	s_and_saveexec_b64 s[44:45], s[76:77]
	s_cbranch_execz .LBB0_293
	s_mov_b64 s[54:55], exec
	v_mbcnt_lo_u32_b32 v0, s54, 0
	v_mbcnt_hi_u32_b32 v0, s55, v0
	v_cmp_eq_u32_e32 vcc, 0, v0
	s_and_saveexec_b64 s[52:53], vcc
	s_cbranch_execz .LBB0_292
	s_bcnt1_i32_b64 s46, s[54:55]
	v_readlane_b32 s54, v252, 14
	v_mov_b32_e32 v2, s46
	v_readlane_b32 s55, v252, 15
	s_nop 4
	global_atomic_add v2, v1, v2, s[54:55] offset:768 sc0

.LBB0_293:
	s_or_b64 exec, exec, s[44:45]
	s_add_i32 s83, 0, 0x23fc0
	s_cmp_lg_u32 s83, -1
	s_cselect_b32 s44, s83, 0
	s_cselect_b32 s45, s79, 0
	v_mov_b32_e32 v2, s44
	v_mov_b32_e32 v3, s45
	s_waitcnt lgkmcnt(0)
	s_barrier
	flat_load_dword v0, v[2:3] sc0 sc1
	s_waitcnt vmcnt(0)
	s_mov_b64 s[44:45], -1
	s_waitcnt lgkmcnt(0)
	v_readfirstlane_b32 s46, v0
	s_cmp_eq_u32 s101, 0
	s_cbranch_scc1 .Lq3_have_u
	s_addk_i32 s46, 0x200
.Lq3_have_u:
	s_cmpk_gt_i32 s46, 0x21f
	s_cbranch_scc1 .LBB0_288
	s_mul_hi_i32 s44, s46, 0x78787879
	s_lshr_b32 s45, s44, 31
	s_ashr_i32 s44, s44, 8
	s_add_i32 s44, s44, s45
	s_mulk_i32 s44, 0x220
	s_sub_i32 s44, s46, s44
	s_bfe_u32 s45, s44, 0x5001a
	s_add_i32 s45, s44, s45
	s_sext_i32_i16 s46, s45
	s_and_b32 s45, s45, 0xffe0
	s_ashr_i32 s46, s46, 5
	s_sub_i32 s44, s44, s45
	s_sub_i32 s46, 16, s46
	s_mul_i32 s44, s44, 17
	s_and_b32 s46, s46, 0xffff
	s_sext_i32_i16 s44, s44
	s_add_i32 s52, s44, s46
	s_mul_i32 s44, s52, 0x7879
	s_sext_i32_i16 s53, s52
	s_lshr_b32 s45, s44, 31
	s_lshr_b32 s44, s44, 20
	s_mulk_i32 s53, 0x7879
	s_add_i32 s44, s44, s45
	s_lshr_b32 s65, s53, 31
	s_ashr_i32 s68, s53, 19
	s_and_b32 s62, s44, 3
	s_mov_b32 s44, 27
	s_add_i32 s68, s68, s65
	s_ashr_i32 s45, s44, 31
	s_and_b32 s64, s68, 1
	s_lshl_b64 s[44:45], s[44:45], 3
	s_add_u32 s44, s0, s44
	s_addc_u32 s45, s1, s45
	s_load_dwordx2 s[54:55], s[44:45], 0x0
	s_mov_b32 s44, 14
	s_mov_b32 s56, 15
	v_readlane_b32 s45, v252, 16
	s_ashr_i32 s57, s56, 31
	s_or_b32 s46, s45, s64
	s_lshl_b32 s63, s62, 6
	s_lshl_b64 s[56:57], s[56:57], 3
	s_add_u32 s56, s0, s56
	s_addc_u32 s57, s1, s57
	s_load_dwordx2 s[56:57], s[56:57], 0x0
	s_and_saveexec_b64 s[58:59], s[38:39]
	s_cbranch_execz .LBB0_299
	s_ashr_i32 s45, s44, 31
	s_lshl_b64 s[44:45], s[44:45], 3
	s_add_u32 s44, s0, s44
	s_addc_u32 s45, s1, s45
	s_load_dwordx2 s[44:45], s[44:45], 0x0
	s_lshl_b64 s[60:61], s[46:47], 14
	v_mov_b32_e32 v4, v62
	s_waitcnt lgkmcnt(0)
	s_add_u32 s44, s44, s60
	s_addc_u32 s45, s45, s61
	s_lshl_b32 s60, s63, 2
	s_add_u32 s44, s44, s60
	s_addc_u32 s45, s45, 0
	s_lshl_b32 s60, s64, 4
	v_subrev_u32_e32 v0, s60, v67
	v_cmp_gt_u32_e32 vcc, 16, v0
	v_lshlrev_b32_e32 v0, 8, v0
	v_lshl_add_u64 v[2:3], v[0:1], 2, s[44:45]
	s_mov_b64 s[60:61], 0
	v_mov_b32_e32 v0, v111
	s_branch .LBB0_297

.LBB0_427:
	s_or_b64 exec, exec, s[2:3]
	s_mov_b32 s2, 27
	s_waitcnt lgkmcnt(0)
	s_barrier
	s_ashr_i32 s3, s2, 31
	s_lshl_b64 s[2:3], s[2:3], 3
	s_add_u32 s2, s0, s2
	s_addc_u32 s3, s1, s3
	s_load_dwordx2 s[2:3], s[2:3], 0x0
	s_mov_b32 s4, 27
	s_waitcnt lgkmcnt(0)
	s_add_u32 s5, s2, 0x7c00000
	v_writelane_b32 v252, s5, 17
	s_addc_u32 s5, s3, 0
	v_writelane_b32 v252, s5, 18
	s_ashr_i32 s5, s4, 31
	s_lshl_b64 s[4:5], s[4:5], 3
	s_add_u32 s4, s0, s4
	s_addc_u32 s5, s1, s5
	s_load_dwordx2 s[4:5], s[4:5], 0x0
	s_waitcnt lgkmcnt(0)
	s_add_u32 s4, s4, 0x16300000
	v_writelane_b32 v252, s4, 19
	s_addc_u32 s4, s5, 0
	v_writelane_b32 v252, s4, 20
	s_nop 0
	v_readlane_b32 s4, v252, 9
	v_readlane_b32 s5, v252, 10
	s_lshl_b64 s[6:7], s[4:5], 11
	v_writelane_b32 v252, s6, 21
	s_lshl_b32 s46, s4, 9
	s_nop 0
	v_writelane_b32 v252, s7, 22
	s_lshl_b64 s[6:7], s[4:5], 9
	v_writelane_b32 v252, s6, 23
	s_add_u32 s2, s2, 0xb390c00
	s_nop 0
	v_writelane_b32 v252, s7, 24
	v_writelane_b32 v252, s2, 25
	s_addc_u32 s2, s3, 0
	v_writelane_b32 v252, s2, 26
	s_lshl_b64 s[2:3], s[46:47], 2
	v_writelane_b32 v252, s2, 27
	s_nop 1
	v_writelane_b32 v252, s3, 28
	v_writelane_b32 v252, s92, 29
	s_nop 1
	v_writelane_b32 v252, s93, 30
	v_writelane_b32 v252, s94, 31
	s_nop 1
	v_writelane_b32 v252, s95, 32
	v_writelane_b32 v252, s83, 33
	s_load_dwordx2 s[100:101], s[0:1], 0xe0
	s_waitcnt lgkmcnt(0)
	s_cmp_eq_u32 s100, 0x100
	s_cselect_b32 s101, 1, 0
	s_cselect_b32 s100, 0, 5
	s_branch .LBB0_430

.LBB0_430:
	s_barrier
	s_cmp_lt_u32 s100, 5
	s_cbranch_scc0 .Lq4_dyn
	v_readlane_b32 s28, v254, 56
	s_lshl_b32 s2, s100, 8
	s_add_i32 s28, s28, s2
	s_cmp_eq_u32 s100, 0
	s_cselect_b32 s2, 0, 16
	s_add_i32 s28, s28, s2
	s_add_i32 s100, s100, 1
	s_mov_b64 s[2:3], -1
	s_branch .Lq4_have_u
.Lq4_dyn:
	s_and_saveexec_b64 s[2:3], s[76:77]
	s_cbranch_execz .LBB0_434
	s_mov_b64 s[6:7], exec
	v_mbcnt_lo_u32_b32 v0, s6, 0
	v_mbcnt_hi_u32_b32 v0, s7, v0
	v_cmp_eq_u32_e32 vcc, 0, v0
	s_and_saveexec_b64 s[4:5], vcc
	s_cbranch_execz .LBB0_433
	s_bcnt1_i32_b64 s6, s[6:7]
	v_mov_b32_e32 v2, s6
	v_readlane_b32 s6, v252, 14
	v_readlane_b32 s7, v252, 15
	s_nop 4
	global_atomic_add v2, v1, v2, s[6:7] offset:256 sc0

.LBB0_434:
	s_or_b64 exec, exec, s[2:3]
	s_cmp_lg_u32 s83, -1
	s_cselect_b32 s2, s83, 0
	s_cselect_b32 s3, s79, 0
	v_mov_b32_e32 v2, s2
	v_mov_b32_e32 v3, s3
	s_waitcnt lgkmcnt(0)
	s_barrier
	flat_load_dword v0, v[2:3] sc0 sc1
	s_waitcnt vmcnt(0)
	s_mov_b64 s[2:3], -1
	s_waitcnt lgkmcnt(0)
	v_readfirstlane_b32 s28, v0
	s_cmp_eq_u32 s101, 0
	s_cbranch_scc1 .Lq4_have_u
	s_addk_i32 s28, 0x500
	s_cmp_lt_u32 s28, 0x510
	s_cbranch_scc0 .Lq4_have_u
	s_sub_i32 s28, s28, 0x400
.Lq4_have_u:
	s_cmpk_gt_i32 s28, 0x10f
	s_cbranch_scc1 .LBB0_529
	s_mul_hi_i32 s2, s28, 0x78787879
	s_lshr_b32 s3, s2, 31
	s_lshr_b32 s2, s2, 7
	s_add_i32 s2, s2, s3
	s_mulk_i32 s2, 0x110
	s_sub_i32 s2, s28, s2
	s_sext_i32_i16 s3, s2
	s_bfe_u32 s3, s3, 0x4001b
	s_add_i32 s3, s2, s3
	s_sext_i32_i16 s4, s3
	s_lshr_b32 s4, s4, 4
	s_sub_i32 s4, 16, s4
	s_and_b32 s5, s4, 0xffff
	s_cmp_eq_u32 s5, 0
	v_readlane_b32 s8, v254, 51
	s_cselect_b64 s[6:7], -1, 0
	v_readlane_b32 s9, v254, 52
	s_and_b64 s[6:7], s[8:9], s[6:7]
	s_and_b64 vcc, exec, s[6:7]
	v_writelane_b32 v252, s28, 34
	s_cbranch_vccnz .LBB0_530
	s_and_b32 s3, s3, 0xfff0
	s_sub_i32 s2, s2, s3
	s_mul_i32 s2, s2, 17
	s_add_i32 s2, s2, s4
	s_sext_i32_i16 s3, s2
	s_mulk_i32 s3, 0x7879
	s_ashr_i32 s4, s3, 19
	s_lshr_b32 s5, s3, 31
	s_add_i32 s4, s4, s5
	s_mul_i32 s6, s4, 17
	s_sub_i32 s6, s2, s6
	s_ashr_i32 s2, s3, 21
	v_mov_b32_e32 v102, v196
	s_and_b32 s11, s4, 3
	s_add_i32 s4, s2, s5
	s_mov_b32 s2, 27
	s_ashr_i32 s3, s2, 31
	v_readfirstlane_b32 s9, v102
	s_ashr_i32 s44, s9, 6
	s_lshl_b64 s[2:3], s[2:3], 3
	s_add_u32 s2, s0, s2
	s_addc_u32 s3, s1, s3
	s_load_dwordx2 s[2:3], s[2:3], 0x0
	v_readlane_b32 s12, v252, 27
	s_sext_i32_i16 s67, s6
	v_readlane_b32 s13, v252, 28
	s_sext_i32_i16 s4, s4
	s_waitcnt lgkmcnt(0)
	s_add_u32 s96, s2, 0x7c00000
	s_mov_b32 s2, 27
	s_addc_u32 s97, s3, 0
	s_ashr_i32 s3, s2, 31
	s_lshl_b64 s[2:3], s[2:3], 3
	s_add_u32 s2, s0, s2
	s_addc_u32 s3, s1, s3
	s_load_dwordx2 s[14:15], s[2:3], 0x0
	s_mov_b32 s2, 16
	s_ashr_i32 s3, s2, 31
	s_lshl_b64 s[2:3], s[2:3], 3
	s_add_u32 s2, s0, s2
	s_addc_u32 s3, s1, s3
	s_load_dwordx2 s[2:3], s[2:3], 0x0
	v_and_b32_e32 v106, 15, v102
	s_mul_i32 s56, s4, 0x2100
	v_and_b32_e32 v3, 7, v102
	v_bfe_u32 v13, v102, 2, 4
	s_waitcnt lgkmcnt(0)
	s_add_u32 s40, s2, s12
	s_addc_u32 s41, s3, s13
	s_lshl_b32 s3, s67, 3
	s_and_b32 s2, s6, 0xffff
	s_add_i32 s5, s3, -4
	s_cmp_lg_u32 s2, 0
	s_cselect_b64 s[2:3], -1, 0
	v_writelane_b32 v252, s2, 35
	v_and_b32_e32 v104, 63, v102
	v_lshrrev_b32_e32 v0, 1, v102
	v_writelane_b32 v252, s3, 36
	s_and_b64 s[2:3], s[2:3], exec
	s_cselect_b32 s2, s5, 0
	s_cselect_b32 s54, 8, 4
	s_add_i32 s57, s2, -1
	v_writelane_b32 v252, s2, 37
	s_add_i32 s2, s57, s54
	v_writelane_b32 v252, s2, 38
	s_movk_i32 s2, 0x800
	v_cmp_gt_i32_e64 s[2:3], s2, v102
	v_and_b32_e32 v15, 12, v13
	v_lshlrev_b32_e32 v12, 2, v106
	v_writelane_b32 v252, s2, 39
	v_lshlrev_b32_e32 v8, 5, v3
	v_ashrrev_i32_e32 v105, 3, v102
	v_writelane_b32 v252, s3, 40
	v_cmp_gt_i32_e64 s[2:3], 64, v102
	v_and_b32_e32 v108, 24, v0
	v_lshlrev_b32_e32 v2, 3, v3
	v_writelane_b32 v252, s2, 41
	v_lshlrev_b32_e32 v0, 2, v104
	v_readlane_b32 s55, v254, 47
	v_writelane_b32 v252, s3, 42
	s_lshl_b32 s2, s4, 3
	s_lshl_b32 s3, s11, 1
	s_or_b32 s61, s3, s2
	s_sub_i32 s2, 17, s67
	v_writelane_b32 v252, s2, 43
	s_lshl_b32 s2, s44, 5
	s_and_b32 s2, s2, 32
	s_lshl_b32 s4, s44, 3
	v_or_b32_e32 v10, s2, v106
	s_lshl_b32 s2, s2, 2
	s_and_b32 s3, s4, -16
	s_add_i32 s2, s2, 0
	v_and_b32_e32 v111, 31, v102
	v_or_b32_e32 v9, s3, v15
	v_add_u32_e32 v127, s2, v12
	s_movk_i32 s2, 0x104
	v_add_u32_e32 v110, 0, v8
	v_add_u32_e32 v109, s55, v0
	v_mul_lo_u32 v19, v9, s2
	v_add_u32_e32 v14, 0, v0
	v_bitop3_b32 v0, v105, v2, 56 bitop3:0x6c
	v_lshlrev_b32_e32 v6, 1, v105
	v_mad_u64_u32 v[112:113], s[2:3], v105, s2, v[110:111]
	v_lshlrev_b32_e32 v4, 4, v3
	v_lshlrev_b32_e32 v0, 1, v0
	v_and_b32_e32 v11, 14, v6
	s_movk_i32 s2, 0x48
	v_add3_u32 v22, 0, v0, v11
	v_mad_u64_u32 v[6:7], s[2:3], v105, s2, v[2:3]
	v_bitop3_b32 v0, v4, 56, v105 bitop3:0x48
	v_lshl_add_u32 v113, v6, 1, 0
	v_lshl_add_u32 v0, v0, 1, 0
	v_mul_u32_u24_e32 v6, 0x900, v3
	v_add3_u32 v129, v0, v6, v11
	v_or_b32_e32 v0, 8, v4
	v_bfe_u32 v18, v102, 1, 5
	v_bitop3_b32 v6, v0, 56, v105 bitop3:0x48
	v_and_b32_e32 v24, 24, v18
	v_lshl_add_u32 v6, v6, 1, 0
	v_mul_u32_u24_e32 v0, 0x90, v0
	v_lshlrev_b32_e32 v25, 1, v24
	v_mul_u32_u24_e32 v7, 0x480, v3
	v_add3_u32 v131, v6, v0, v11
	v_bfi_b32 v0, -16, s4, v102
	v_add_u32_e32 v6, 0, v25
	s_movk_i32 s46, 0x90
	v_mad_u64_u32 v[114:115], s[2:3], v0, s46, v[6:7]
	v_cmp_ge_i32_e64 s[2:3], v10, v9
	s_ashr_i32 s45, s44, 31
	s_lshl_b32 s48, s44, 4
	v_writelane_b32 v252, s2, 44
	s_lshl_b32 s58, s11, 6
	s_lshl_b32 s8, s11, 7
	v_writelane_b32 v252, s3, 45
	v_cmp_le_i32_e64 s[2:3], v10, v9
	s_lshl_b64 s[94:95], s[44:45], 12
	s_lshl_b32 s59, s44, 8
	v_writelane_b32 v252, s2, 46
	v_or_b32_e32 v29, 1, v9
	s_ashr_i32 s49, s48, 31
	v_writelane_b32 v252, s3, 47
	v_cmp_gt_i32_e64 s[2:3], v10, v9
	s_cmp_lt_i32 s44, 0
	v_or_b32_e32 v30, 2, v9
	v_writelane_b32 v252, s2, 48
	s_cselect_b64 s[50:51], -1, 0
	s_cmp_gt_i32 s44, 0
	v_writelane_b32 v252, s3, 49
	v_cmp_le_i32_e64 s[2:3], v10, v29
	s_cselect_b64 s[34:35], -1, 0
	s_cmp_lt_i32 s44, 1
	v_writelane_b32 v252, s2, 50
	s_cselect_b64 s[12:13], -1, 0
	s_cmp_gt_i32 s44, 1
	v_writelane_b32 v252, s3, 51
	v_cmp_ge_i32_e64 s[2:3], v10, v30
	s_cselect_b64 s[4:5], -1, 0
	s_cmp_lt_i32 s44, 2
	v_writelane_b32 v252, s2, 52
	v_or_b32_e32 v31, 3, v9
	s_cselect_b64 s[36:37], -1, 0
	v_writelane_b32 v252, s3, 53
	v_cmp_le_i32_e64 s[2:3], v10, v30
	s_cmp_gt_i32 s44, 2
	s_cselect_b64 s[28:29], -1, 0
	v_writelane_b32 v252, s2, 54
	s_cmp_lt_i32 s44, 3
	s_cselect_b64 s[30:31], -1, 0
	v_writelane_b32 v252, s3, 55
	v_cmp_ge_i32_e64 s[2:3], v10, v31
	s_cmp_gt_i32 s44, 3
	s_cselect_b64 s[6:7], -1, 0
	v_writelane_b32 v252, s2, 56
	s_cmp_lt_i32 s44, 4
	s_cselect_b64 s[24:25], -1, 0
	v_writelane_b32 v252, s3, 57
	v_cmp_le_i32_e64 s[2:3], v10, v31
	s_cmp_gt_i32 s44, 4
	v_or_b32_e32 v0, s8, v4
	v_writelane_b32 v252, s2, 58
	v_lshlrev_b32_e32 v0, 2, v0
	v_lshl_add_u64 v[116:117], s[40:41], 0, v[0:1]
	v_writelane_b32 v252, s3, 59
	s_cselect_b64 s[2:3], -1, 0
	s_cmp_lt_i32 s44, 5
	s_cselect_b64 s[26:27], -1, 0
	s_cmp_gt_i32 s44, 5
	s_cselect_b64 s[20:21], -1, 0
	s_cmp_lt_i32 s44, 6
	s_cselect_b64 s[22:23], -1, 0
	s_cmp_gt_i32 s44, 6
	s_cselect_b64 s[18:19], -1, 0
	s_cmp_lt_i32 s44, 7
	s_cselect_b64 s[38:39], -1, 0
	s_cmp_gt_i32 s44, 7
	s_cselect_b64 s[40:41], -1, 0
	s_andn2_b32 s9, s9, 63
	s_add_i32 s9, s55, s9
	s_lshl_b32 s11, s11, 8
	s_add_u32 s11, s14, s11
	s_addc_u32 s15, s15, 0
	s_add_u32 s14, s11, 0x16300000
	v_or_b32_e32 v20, 16, v10
	v_or_b32_e32 v33, s48, v15
	v_or_b32_e32 v34, s48, v106
	s_addc_u32 s15, s15, 0
	s_lshl_b64 s[48:49], s[48:49], 1
	v_mul_lo_u32 v28, v9, s46
	v_cmp_ge_i32_e64 s[52:53], v20, v9
	s_add_u32 s48, s14, s48
	v_cmp_le_i32_e64 s[62:63], v20, v9
	v_cmp_gt_i32_e64 s[64:65], v20, v9
	v_mov_b32_e32 v9, v1
	v_lshlrev_b32_e32 v17, 6, v10
	v_lshl_add_u32 v125, v10, 2, 0
	v_mul_u32_u24_e32 v26, 0x90, v10
	v_lshl_add_u32 v27, v10, 1, 0
	s_addc_u32 s49, s15, s49
	v_lshlrev_b32_e32 v10, 1, v106
	v_mov_b32_e32 v11, v1
	v_lshl_add_u64 v[120:121], s[14:15], 0, v[8:9]
	v_add_u32_e32 v9, s9, v12
	v_readlane_b32 s9, v254, 49
	v_mul_lo_u32 v0, v34, s46
	v_or_b32_e32 v122, 48, v104
	v_lshl_add_u64 v[118:119], s[48:49], 0, v[10:11]
	v_add_u32_e32 v11, s9, v10
	v_add3_u32 v180, s9, v0, v25
	v_mul_u32_u24_e32 v25, 0x48, v122
	v_readlane_b32 s9, v254, 48
	v_writelane_b32 v252, s52, 60
	v_add_u32_e32 v10, 0, v0
	v_mul_u32_u24_e32 v0, 0x48, v106
	v_lshl_add_u32 v188, v25, 1, v6
	v_add_u32_e32 v189, s9, v12
	v_bitop3_b32 v12, v34, v24, 56 bitop3:0x6c
	v_and_b32_e32 v25, 8, v102
	v_writelane_b32 v252, s53, 61
	v_cmp_le_i32_e64 s[52:53], v20, v29
	v_mul_lo_u32 v29, v33, s46
	v_lshl_add_u32 v181, v0, 1, v6
	v_bitop3_b32 v0, v34, 56, v18 bitop3:0x48
	v_lshl_add_u32 v190, v12, 1, v10
	v_mad_u32_u24 v12, v106, s46, 0
	v_bitop3_b32 v33, v18, v25, 24 bitop3:0x6c
	v_lshl_add_u32 v186, v0, 1, v10
	v_or_b32_e32 v0, 32, v18
	v_lshl_add_u32 v191, v33, 1, v12
	v_or_b32_e32 v33, 32, v24
	v_bitop3_b32 v0, v34, 56, v0 bitop3:0x48
	v_bitop3_b32 v33, v34, v33, 56 bitop3:0x6c
	v_lshl_add_u32 v187, v0, 1, v10
	v_or_b32_e32 v0, 16, v106
	v_lshl_add_u32 v192, v33, 1, v10
	v_bitop3_b32 v10, v24, v25, 32 bitop3:0x36
	v_lshl_add_u32 v193, v10, 1, v12
	v_add_u32_e32 v10, 0x900, v12
	v_bitop3_b32 v25, v106, 24, 16 bitop3:0xc8
	v_bitop3_b32 v0, v0, v18, 24 bitop3:0x28
	v_lshl_add_u32 v194, v0, 1, v10
	v_bitop3_b32 v0, v24, v25, 32 bitop3:0x36
	s_mul_i32 s45, s44, 0x820
	v_lshl_add_u32 v195, v0, 1, v10
	v_bitop3_b32 v10, v106, 40, 32 bitop3:0xc8
	v_add_u32_e32 v115, s45, v14
	v_or_b32_e32 v14, 32, v106
	v_add_u32_e32 v0, 0x1200, v12
	v_bitop3_b32 v10, v24, v10, 32 bitop3:0x36
	v_bitop3_b32 v12, v14, v24, 40 bitop3:0x6c
	v_lshl_add_u32 v212, v10, 1, v0
	v_bitop3_b32 v10, v104, 56, 48 bitop3:0xc8
	v_or_b32_e32 v16, 1, v2
	v_lshl_add_u32 v211, v12, 1, v0
	v_mad_u32_u24 v0, v122, s46, 0
	v_bitop3_b32 v12, v18, v10, 24 bitop3:0x6c
	v_bitop3_b32 v10, v24, v10, 32 bitop3:0x36
	v_lshl_add_u32 v213, v12, 1, v0
	v_lshl_add_u32 v214, v10, 1, v0
	v_add_u32_e32 v215, s9, v8
	v_lshl_add_u32 v216, v16, 2, s9
	v_or_b32_e32 v0, 3, v13
	s_movk_i32 s9, 0x600
	v_or_b32_e32 v8, 19, v13
	v_or_b32_e32 v14, 35, v13
	v_mul_u32_u24_e32 v23, 0x90, v16
	v_mul_u32_u24_e32 v126, 0x600, v0
	v_mul_u32_u24_e32 v25, 0x210, v0
	v_mad_u32_u24 v0, v15, s9, v202
	v_mul_u32_u24_e32 v128, 0x600, v8
	v_mul_u32_u24_e32 v33, 0x210, v8
	v_mad_u32_u24 v8, v15, s9, v203
	v_mad_u32_u24 v10, v15, s9, v204
	v_mad_u32_u24 v12, v15, s9, v205
	v_mul_u32_u24_e32 v130, 0x600, v14
	v_mul_u32_u24_e32 v34, 0x210, v14
	v_mad_u32_u24 v14, v15, s9, v206
	v_mad_u32_u24 v16, v15, s9, v207
	v_mad_u32_u24 v18, v15, s9, v208
	s_movk_i32 s9, 0x210
	v_and_b32_e32 v5, 48, v102
	v_mul_u32_u24_e32 v124, 0x600, v15
	v_mul_u32_u24_e32 v24, 0x210, v15
	v_or_b32_e32 v13, 51, v13
	v_mul_lo_u32 v15, v105, s9
	v_add_u32_e32 v5, 0, v5
	v_lshlrev_b32_e32 v21, 6, v20
	v_mul_u32_u24_e32 v32, 0x90, v20
	v_mul_u32_u24_e32 v132, 0x600, v13
	v_mul_u32_u24_e32 v13, 0x210, v13
	v_add_u32_e32 v15, s55, v15
	v_lshlrev_b32_e32 v3, 6, v3
	s_mov_b32 s10, 0
	v_bfi_b32 v107, -16, v105, v102
	v_ashrrev_i32_e32 v103, 31, v102
	v_lshl_add_u32 v123, v102, 2, 0
	v_cmp_gt_u32_e64 s[42:43], 8, v102
	v_add_u32_e32 v133, 0x120, v131
	v_add_u32_e32 v178, 0x240, v131
	v_add_u32_e32 v179, 0x360, v131
	v_cmp_ge_i32_e64 s[68:69], v20, v30
	v_add_u32_e32 v217, 8, v215
	v_add_u32_e32 v218, 12, v215
	v_add_u32_e32 v219, 16, v215
	v_add_u32_e32 v220, 20, v215
	v_add_u32_e32 v221, 24, v215
	v_add_u32_e32 v222, 28, v215
	v_lshl_add_u32 v223, v102, 1, 0
	v_lshlrev_b32_e32 v134, 1, v2
	v_lshlrev_b32_e32 v136, 1, v4
	v_add_u32_e32 v224, v5, v17
	v_add_u32_e32 v225, v127, v19
	v_add_u32_e32 v226, v5, v21
	v_add_u32_e32 v227, v22, v7
	v_add_u32_e32 v228, v6, v26
	v_add_u32_e32 v229, v27, v28
	v_add_u32_e32 v230, v6, v32
	v_add_u32_e32 v231, v11, v29
	v_add_u32_e32 v232, v9, v24
	v_add_u32_e32 v233, v9, v25
	v_lshlrev_b32_e32 v138, 1, v0
	v_add_u32_e32 v234, v9, v33
	v_lshlrev_b32_e32 v140, 1, v8
	v_lshlrev_b32_e32 v142, 1, v10
	v_lshlrev_b32_e32 v144, 1, v12
	v_add_u32_e32 v235, v9, v34
	v_lshlrev_b32_e32 v146, 1, v14
	v_lshlrev_b32_e32 v148, 1, v16
	v_lshlrev_b32_e32 v150, 1, v18
	v_add_u32_e32 v236, v9, v13
	v_add_u32_e32 v237, v15, v3
	v_add_u32_e32 v238, v22, v23
	s_lshl_b32 s14, s8, 1
	v_cmp_le_i32_e64 s[70:71], v20, v30
	v_cmp_ge_i32_e64 s[72:73], v20, v31
	v_cmp_le_i32_e64 s[74:75], v20, v31
	s_mov_b64 s[44:45], -1
	s_mov_b32 s60, s58
	s_lshl_b32 s46, s58, 1
	s_branch .LBB0_438

.LBB0_533:
	v_add_u32_e32 v0, s4, v222
	ds_read_b64_tr_b16 v[178:179], v0 offset:24576
	ds_read_b64_tr_b16 v[180:181], v0 offset:25088
	s_waitcnt lgkmcnt(9)
	v_mfma_f32_32x32x16_bf16 v[98:113], v[174:177], v[142:145], v[34:49]
	v_add_f32_e32 v82, v66, v67
	v_add_f32_e32 v82, v68, v82
	v_add_f32_e32 v82, v69, v82
	v_add_f32_e32 v82, v70, v82
	v_add_f32_e32 v82, v71, v82
	v_cvt_pk_bf16_f32 v134, v66, v67
	v_cvt_pk_bf16_f32 v135, v68, v69
	ds_read_b64_tr_b16 v[174:175], v0 offset:28672
	ds_read_b64_tr_b16 v[176:177], v0 offset:29184
	v_add_f32_e32 v66, v72, v82
	s_waitcnt lgkmcnt(10)
	v_mfma_f32_32x32x16_bf16 v[82:97], v[170:173], v[142:145], v[34:49]
	v_add_f32_e32 v66, v73, v66
	v_add_f32_e32 v66, v74, v66
	v_add_f32_e32 v114, v75, v66
	v_cvt_pk_bf16_f32 v136, v70, v71
	v_cvt_pk_bf16_f32 v137, v72, v73
	ds_read_b64_tr_b16 v[66:67], v0 offset:25600
	ds_read_b64_tr_b16 v[68:69], v0 offset:26112
	s_waitcnt lgkmcnt(11)
	v_mfma_f32_32x32x16_bf16 v[98:113], v[166:169], v[138:141], v[98:113]
	v_add_f32_e32 v70, v76, v114
	v_add_f32_e32 v70, v77, v70
	v_add_f32_e32 v70, v78, v70
	v_add_f32_e32 v114, v79, v70
	v_cvt_pk_bf16_f32 v126, v74, v75
	v_cvt_pk_bf16_f32 v127, v76, v77
	ds_read_b64_tr_b16 v[70:71], v0 offset:29696
	ds_read_b64_tr_b16 v[72:73], v0 offset:30208
	s_waitcnt lgkmcnt(12)
	v_mfma_f32_32x32x16_bf16 v[82:97], v[162:165], v[138:141], v[82:97]
	v_add_f32_e32 v74, v80, v114
	v_add_f32_e32 v74, v81, v74
	v_add_f32_e32 v74, v50, v74
	v_add_f32_e32 v114, v51, v74
	v_cvt_pk_bf16_f32 v128, v78, v79
	v_cvt_pk_bf16_f32 v129, v80, v81
	ds_read_b64_tr_b16 v[74:75], v0 offset:26624
	ds_read_b64_tr_b16 v[76:77], v0 offset:27136
	s_waitcnt lgkmcnt(13)
	v_mfma_f32_32x32x16_bf16 v[98:113], v[158:161], v[130:133], v[98:113]
	v_add_f32_e32 v78, v52, v114
	v_add_f32_e32 v78, v53, v78
	v_add_f32_e32 v78, v54, v78
	v_add_f32_e32 v78, v55, v78
	v_cvt_pk_bf16_f32 v118, v50, v51
	v_cvt_pk_bf16_f32 v119, v52, v53
	ds_read_b64_tr_b16 v[50:51], v0 offset:30720
	ds_read_b64_tr_b16 v[52:53], v0 offset:31232
	s_waitcnt lgkmcnt(14)
	v_mfma_f32_32x32x16_bf16 v[82:97], v[154:157], v[130:133], v[82:97]
	v_add_f32_e32 v78, v56, v78
	v_add_f32_e32 v78, v57, v78
	v_add_f32_e32 v78, v58, v78
	v_add_f32_e32 v78, v59, v78
	v_cvt_pk_bf16_f32 v120, v54, v55
	v_cvt_pk_bf16_f32 v121, v56, v57
	ds_read_b64_tr_b16 v[54:55], v0 offset:27648
	ds_read_b64_tr_b16 v[56:57], v0 offset:28160
	s_waitcnt lgkmcnt(14)
	v_mfma_f32_32x32x16_bf16 v[98:113], v[150:153], v[122:125], v[98:113]
	v_add_f32_e32 v78, v60, v78
	v_add_f32_e32 v78, v61, v78
	v_add_f32_e32 v78, v62, v78
	v_add_f32_e32 v78, v63, v78
	v_cvt_pk_bf16_f32 v114, v58, v59
	v_cvt_pk_bf16_f32 v115, v60, v61
	ds_read_b64_tr_b16 v[58:59], v0 offset:31744
	ds_read_b64_tr_b16 v[60:61], v0 offset:32256
	v_mfma_f32_32x32x16_bf16 v[82:97], v[146:149], v[122:125], v[82:97]
	v_add_f32_e32 v0, v64, v78
	v_add_f32_e32 v0, v65, v0
	v_add_f32_e32 v0, 0, v0
	v_cvt_pk_bf16_f32 v116, v62, v63
	v_cvt_pk_bf16_f32 v117, v64, v65
	v_lshl_add_u64 v[62:63], v[194:195], 0, s[88:89]
	s_add_i32 s4, s23, s20
	s_mov_b32 s5, m0
	s_mov_b32 m0, s4
	s_nop 0
	global_load_lds_dwordx4 v[62:63], off
	s_mov_b32 m0, s5
	v_lshl_add_u64 v[62:63], v[192:193], 0, s[88:89]
	s_add_i32 s4, s22, s21
	s_mov_b32 s5, m0
	s_mov_b32 m0, s4
	s_nop 0
	global_load_lds_dwordx4 v[62:63], off
	s_mov_b32 m0, s5
	v_max_f32_e32 v62, v98, v99
	v_max3_f32 v63, v100, v101, v83
	v_max3_f32 v62, v62, v82, v84
	v_max3_f32 v62, v62, v85, v102
	v_max3_f32 v63, v63, v104, v105
	v_max3_f32 v62, v62, v103, v86
	v_max3_f32 v63, v63, v88, v89
	v_max3_f32 v62, v62, v87, v106
	v_max3_f32 v63, v63, v108, v109
	v_max3_f32 v62, v62, v107, v90
	v_max3_f32 v63, v63, v92, v93
	v_max3_f32 v62, v62, v91, v110
	v_max3_f32 v63, v63, v112, v113
	v_max3_f32 v62, v62, v111, v94
	v_max3_f32 v63, v63, v96, v97
	v_max3_f32 v62, v62, v95, v63
	v_mov_b32_e32 v63, v62
	s_nop 1
	v_permlane32_swap_b32_e32 v62, v63
	v_max_f32_e32 v62, v62, v63
	v_cmp_lt_f32_e32 vcc, s82, v62
	s_cmp_lg_u64 vcc, 0
	v_add_f32_e32 v0, v223, v0
	s_cselect_b64 s[4:5], -1, 0
	s_cbranch_vccnz .LBB0_541

.LBB0_536:
	s_add_i32 s4, s22, 0x2000
	s_cmpk_lg_i32 s22, 0x4000
	s_cselect_b32 s24, s4, 0
	v_add_u32_e32 v189, s23, v222
	ds_read_b64_tr_b16 v[150:151], v189 offset:24576
	ds_read_b64_tr_b16 v[152:153], v189 offset:25088
	s_waitcnt lgkmcnt(9)
	v_mfma_f32_32x32x16_bf16 v[66:81], v[62:65], v[142:145], v[34:49]
	v_add_f32_e32 v50, v98, v99
	v_add_f32_e32 v50, v100, v50
	v_add_f32_e32 v50, v101, v50
	v_add_f32_e32 v50, v102, v50
	v_add_f32_e32 v50, v103, v50
	v_cvt_pk_bf16_f32 v134, v98, v99
	v_cvt_pk_bf16_f32 v135, v100, v101
	ds_read_b64_tr_b16 v[146:147], v189 offset:28672
	ds_read_b64_tr_b16 v[148:149], v189 offset:29184
	v_add_f32_e32 v50, v104, v50
	v_add_f32_e32 v50, v105, v50
	v_add_f32_e32 v50, v106, v50
	v_add_f32_e32 v114, v107, v50
	s_waitcnt lgkmcnt(10)
	v_mfma_f32_32x32x16_bf16 v[50:65], v[174:177], v[142:145], v[34:49]
	v_cvt_pk_bf16_f32 v136, v102, v103
	v_cvt_pk_bf16_f32 v137, v104, v105
	ds_read_b64_tr_b16 v[98:99], v189 offset:25600
	ds_read_b64_tr_b16 v[100:101], v189 offset:26112
	s_waitcnt lgkmcnt(11)
	v_mfma_f32_32x32x16_bf16 v[66:81], v[178:181], v[138:141], v[66:81]
	v_add_f32_e32 v102, v108, v114
	v_add_f32_e32 v102, v109, v102
	v_add_f32_e32 v102, v110, v102
	v_add_f32_e32 v114, v111, v102
	v_cvt_pk_bf16_f32 v126, v106, v107
	v_cvt_pk_bf16_f32 v127, v108, v109
	ds_read_b64_tr_b16 v[102:103], v189 offset:29696
	ds_read_b64_tr_b16 v[104:105], v189 offset:30208
	s_waitcnt lgkmcnt(12)
	v_mfma_f32_32x32x16_bf16 v[50:65], v[170:173], v[138:141], v[50:65]
	v_add_f32_e32 v106, v112, v114
	v_add_f32_e32 v106, v113, v106
	v_add_f32_e32 v106, v82, v106
	v_add_f32_e32 v114, v83, v106
	v_cvt_pk_bf16_f32 v128, v110, v111
	v_cvt_pk_bf16_f32 v129, v112, v113
	ds_read_b64_tr_b16 v[106:107], v189 offset:26624
	ds_read_b64_tr_b16 v[108:109], v189 offset:27136
	s_waitcnt lgkmcnt(13)
	v_mfma_f32_32x32x16_bf16 v[66:81], v[166:169], v[130:133], v[66:81]
	v_add_f32_e32 v110, v84, v114
	v_add_f32_e32 v110, v85, v110
	v_add_f32_e32 v110, v86, v110
	v_add_f32_e32 v110, v87, v110
	v_cvt_pk_bf16_f32 v118, v82, v83
	v_cvt_pk_bf16_f32 v119, v84, v85
	ds_read_b64_tr_b16 v[82:83], v189 offset:30720
	ds_read_b64_tr_b16 v[84:85], v189 offset:31232
	s_waitcnt lgkmcnt(14)
	v_mfma_f32_32x32x16_bf16 v[50:65], v[162:165], v[130:133], v[50:65]
	v_add_f32_e32 v110, v88, v110
	v_add_f32_e32 v110, v89, v110
	v_add_f32_e32 v110, v90, v110
	v_add_f32_e32 v110, v91, v110
	v_cvt_pk_bf16_f32 v120, v86, v87
	v_cvt_pk_bf16_f32 v121, v88, v89
	ds_read_b64_tr_b16 v[86:87], v189 offset:27648
	ds_read_b64_tr_b16 v[88:89], v189 offset:28160
	s_waitcnt lgkmcnt(14)
	v_mfma_f32_32x32x16_bf16 v[66:81], v[158:161], v[122:125], v[66:81]
	v_add_f32_e32 v110, v92, v110
	v_add_f32_e32 v110, v93, v110
	v_add_f32_e32 v110, v94, v110
	v_add_f32_e32 v110, v95, v110
	v_cvt_pk_bf16_f32 v114, v90, v91
	v_cvt_pk_bf16_f32 v115, v92, v93
	ds_read_b64_tr_b16 v[90:91], v189 offset:31744
	ds_read_b64_tr_b16 v[92:93], v189 offset:32256
	v_mfma_f32_32x32x16_bf16 v[50:65], v[154:157], v[122:125], v[50:65]
	v_add_f32_e32 v110, v96, v110
	v_add_f32_e32 v110, v97, v110
	v_add_f32_e32 v110, 0, v110
	v_cvt_pk_bf16_f32 v116, v94, v95
	v_cvt_pk_bf16_f32 v117, v96, v97
	v_max_f32_e32 v94, v67, v67
	v_max_f32_e32 v95, v66, v66
	v_max_f32_e32 v94, v95, v94
	s_nop 3
	v_max3_f32 v95, v68, v69, v51
	v_max3_f32 v94, v94, v50, v52
	v_max3_f32 v94, v94, v53, v70
	v_max3_f32 v95, v95, v72, v73
	v_max3_f32 v94, v94, v71, v54
	v_max3_f32 v95, v95, v56, v57
	v_max3_f32 v94, v94, v55, v74
	v_max3_f32 v95, v95, v76, v77
	v_max3_f32 v94, v94, v75, v58
	v_max3_f32 v95, v95, v60, v61
	v_max3_f32 v94, v94, v59, v78
	v_max3_f32 v95, v95, v80, v81
	v_max3_f32 v94, v94, v79, v62
	v_max3_f32 v95, v95, v64, v65
	v_add_f32_e32 v223, v0, v110
	v_max3_f32 v0, v94, v63, v95
	v_mov_b32_e32 v94, v0
	s_nop 1
	v_permlane32_swap_b32_e32 v0, v94
	s_add_i32 s4, s22, s20
	s_mov_b32 s5, m0
	s_mov_b32 m0, s4
	s_nop 0
	global_load_lds_dwordx4 v[194:195], off
	s_mov_b32 m0, s5
	v_max_f32_e32 v0, v0, v94
	s_add_i32 s4, s24, s21
	s_mov_b32 s5, m0
	s_mov_b32 m0, s4
	s_nop 0
	global_load_lds_dwordx4 v[192:193], off
	s_mov_b32 m0, s5
	v_cmp_lt_f32_e32 vcc, s82, v0
	s_cmp_lg_u64 vcc, 0
	s_cselect_b64 s[4:5], -1, 0
	s_cbranch_vccnz .LBB0_544

	.amdhsa_kernel _Z14fwd_megakernel5KArgs
		.amdhsa_group_segment_fixed_size 0
		.amdhsa_private_segment_fixed_size 0
		.amdhsa_kernarg_size 480
		.amdhsa_user_sgpr_count 2
		.amdhsa_user_sgpr_dispatch_ptr 0
		.amdhsa_user_sgpr_queue_ptr 0
		.amdhsa_user_sgpr_kernarg_segment_ptr 1
		.amdhsa_user_sgpr_dispatch_id 0
		.amdhsa_user_sgpr_kernarg_preload_length 0
		.amdhsa_user_sgpr_kernarg_preload_offset 0
		.amdhsa_user_sgpr_private_segment_size 0
		.amdhsa_uses_dynamic_stack 0
		.amdhsa_enable_private_segment 0
		.amdhsa_system_sgpr_workgroup_id_x 1
		.amdhsa_system_sgpr_workgroup_id_y 0
		.amdhsa_system_sgpr_workgroup_id_z 0
		.amdhsa_system_sgpr_workgroup_info 0
		.amdhsa_system_vgpr_workitem_id 2
		.amdhsa_next_free_vgpr 255
		.amdhsa_next_free_sgpr 102
		.amdhsa_accum_offset 256
		.amdhsa_reserve_vcc 1
		.amdhsa_float_round_mode_32 0
		.amdhsa_float_round_mode_16_64 0
		.amdhsa_float_denorm_mode_32 3
		.amdhsa_float_denorm_mode_16_64 3
		.amdhsa_dx10_clamp 1
		.amdhsa_ieee_mode 1
		.amdhsa_fp16_overflow 0
		.amdhsa_tg_split 0
		.amdhsa_exception_fp_ieee_invalid_op 0
		.amdhsa_exception_fp_denorm_src 0
		.amdhsa_exception_fp_ieee_div_zero 0
		.amdhsa_exception_fp_ieee_overflow 0
		.amdhsa_exception_fp_ieee_underflow 0
		.amdhsa_exception_fp_ieee_inexact 0
		.amdhsa_exception_int_div_zero 0
	.end_amdhsa_kernel

amdhsa.kernels:
  - .agpr_count:     0
    .args:
      - .offset:         0
        .size:           224
        .value_kind:     by_value
      - .offset:         224
        .size:           4
        .value_kind:     hidden_block_count_x
      - .offset:         228
        .size:           4
        .value_kind:     hidden_block_count_y
      - .offset:         232
        .size:           4
        .value_kind:     hidden_block_count_z
      - .offset:         236
        .size:           2
        .value_kind:     hidden_group_size_x
      - .offset:         238
        .size:           2
        .value_kind:     hidden_group_size_y
      - .offset:         240
        .size:           2
        .value_kind:     hidden_group_size_z
      - .offset:         242
        .size:           2
        .value_kind:     hidden_remainder_x
      - .offset:         244
        .size:           2
        .value_kind:     hidden_remainder_y
      - .offset:         246
        .size:           2
        .value_kind:     hidden_remainder_z
      - .offset:         264
        .size:           8
        .value_kind:     hidden_global_offset_x
      - .offset:         272
        .size:           8
        .value_kind:     hidden_global_offset_y
      - .offset:         280
        .size:           8
        .value_kind:     hidden_global_offset_z
      - .offset:         288
        .size:           2
        .value_kind:     hidden_grid_dims
      - .offset:         312
        .size:           8
        .value_kind:     hidden_multigrid_sync_arg
      - .offset:         344
        .size:           4
        .value_kind:     hidden_dynamic_lds_size
    .group_segment_fixed_size: 0
    .kernarg_segment_align: 8
    .kernarg_segment_size: 480
    .language:       OpenCL C
    .language_version:
      - 2
      - 0
    .max_flat_workgroup_size: 512
    .name:           _Z14fwd_megakernel5KArgs
    .private_segment_fixed_size: 0
    .sgpr_count:     108
    .sgpr_spill_count: 196
    .symbol:         _Z14fwd_megakernel5KArgs.kd
    .uniform_work_group_size: 1
    .uses_dynamic_stack: false
    .vgpr_count:     255
    .vgpr_spill_count: 0
    .wavefront_size: 64
